# scan decay factored out over groups of 4 tokens (prep emits D-scaled operands, scan multiplies S by D once per 4 steps instead of w every step)
# speedup vs baseline: 1.0253x; 1.0253x over previous
.LBB0_787:
	global_load_dwordx4 v[108:111], v[114:115], off
	s_add_i32 s34, s6, 2
	s_cmp_ge_u32 s34, s43
	s_cbranch_scc1 .LBB0_784
	s_bitcmp1_b32 s34, 0
	s_cselect_b32 s34, 0xe180, 0
	s_add_i32 s34, s34, 16
	v_lshlrev_b32_e32 v136, 2, v118
	v_add3_u32 v142, s34, v136, v149
	s_waitcnt vmcnt(8)
	v_lshlrev_b32_e32 v136, 16, v72
	v_and_b32_e32 v137, 0xffff0000, v72
	v_lshlrev_b32_e32 v138, 16, v68
	v_and_b32_e32 v139, 0xffff0000, v68
	v_pk_add_f32 v[136:137], v[136:137], v[138:139] neg_lo:[0,1] neg_hi:[0,1]
	v_lshlrev_b32_e32 v140, 16, v69
	v_pk_fma_f32 v[136:137], v[4:5], v[136:137], v[138:139]
	v_lshlrev_b32_e32 v138, 16, v73
	v_and_b32_e32 v139, 0xffff0000, v73
	v_and_b32_e32 v141, 0xffff0000, v69
	v_pk_add_f32 v[138:139], v[138:139], v[140:141] neg_lo:[0,1] neg_hi:[0,1]
	s_waitcnt vmcnt(2)
	v_lshlrev_b32_e32 v145, 16, v96
	v_pk_fma_f32 v[138:139], v[6:7], v[138:139], v[140:141]
	ds_write_b128 v142, v[136:139] offset:32768
	v_lshlrev_b32_e32 v136, 16, v74
	v_and_b32_e32 v137, 0xffff0000, v74
	v_lshlrev_b32_e32 v138, 16, v70
	v_and_b32_e32 v139, 0xffff0000, v70
	v_pk_add_f32 v[136:137], v[136:137], v[138:139] neg_lo:[0,1] neg_hi:[0,1]
	v_lshlrev_b32_e32 v140, 16, v71
	v_pk_fma_f32 v[136:137], v[8:9], v[136:137], v[138:139]
	v_lshlrev_b32_e32 v138, 16, v75
	v_and_b32_e32 v139, 0xffff0000, v75
	v_and_b32_e32 v141, 0xffff0000, v71
	v_pk_add_f32 v[138:139], v[138:139], v[140:141] neg_lo:[0,1] neg_hi:[0,1]
	v_lshlrev_b32_e32 v143, 16, v94
	v_pk_fma_f32 v[138:139], v[10:11], v[138:139], v[140:141]
	ds_write_b128 v142, v[136:139] offset:32784
	v_lshlrev_b32_e32 v136, 16, v80
	v_and_b32_e32 v137, 0xffff0000, v80
	v_lshlrev_b32_e32 v138, 16, v76
	v_and_b32_e32 v139, 0xffff0000, v76
	v_pk_add_f32 v[136:137], v[136:137], v[138:139] neg_lo:[0,1] neg_hi:[0,1]
	v_lshlrev_b32_e32 v140, 16, v77
	v_pk_fma_f32 v[136:137], v[44:45], v[136:137], v[138:139]
	v_lshlrev_b32_e32 v138, 16, v81
	v_and_b32_e32 v139, 0xffff0000, v81
	v_and_b32_e32 v141, 0xffff0000, v77
	v_pk_add_f32 v[138:139], v[138:139], v[140:141] neg_lo:[0,1] neg_hi:[0,1]
	v_lshlrev_b32_e32 v144, 16, v98
	v_pk_fma_f32 v[138:139], v[46:47], v[138:139], v[140:141]
	ds_write_b128 v142, v[136:139] offset:24576
	v_lshlrev_b32_e32 v136, 16, v82
	v_and_b32_e32 v137, 0xffff0000, v82
	v_lshlrev_b32_e32 v138, 16, v78
	v_and_b32_e32 v139, 0xffff0000, v78
	v_pk_add_f32 v[136:137], v[136:137], v[138:139] neg_lo:[0,1] neg_hi:[0,1]
	v_lshlrev_b32_e32 v140, 16, v79
	v_pk_fma_f32 v[136:137], v[48:49], v[136:137], v[138:139]
	v_lshlrev_b32_e32 v138, 16, v83
	v_and_b32_e32 v139, 0xffff0000, v83
	v_and_b32_e32 v141, 0xffff0000, v79
	v_pk_add_f32 v[138:139], v[138:139], v[140:141] neg_lo:[0,1] neg_hi:[0,1]
	v_sub_f32_e32 v144, v144, v143
	v_pk_fma_f32 v[138:139], v[50:51], v[138:139], v[140:141]
	ds_write_b128 v142, v[136:139] offset:24592
	v_lshlrev_b32_e32 v136, 16, v88
	v_and_b32_e32 v137, 0xffff0000, v88
	v_lshlrev_b32_e32 v138, 16, v84
	v_and_b32_e32 v139, 0xffff0000, v84
	v_pk_add_f32 v[136:137], v[136:137], v[138:139] neg_lo:[0,1] neg_hi:[0,1]
	v_lshlrev_b32_e32 v140, 16, v85
	v_pk_fma_f32 v[136:137], v[52:53], v[136:137], v[138:139]
	v_lshlrev_b32_e32 v138, 16, v89
	v_and_b32_e32 v139, 0xffff0000, v89
	v_and_b32_e32 v141, 0xffff0000, v85
	v_pk_add_f32 v[138:139], v[138:139], v[140:141] neg_lo:[0,1] neg_hi:[0,1]
	v_fmac_f32_e32 v143, v16, v144
	v_pk_fma_f32 v[138:139], v[54:55], v[138:139], v[140:141]
	ds_write_b128 v142, v[136:139] offset:40960
	v_lshlrev_b32_e32 v136, 16, v90
	v_and_b32_e32 v137, 0xffff0000, v90
	v_lshlrev_b32_e32 v138, 16, v86
	v_and_b32_e32 v139, 0xffff0000, v86
	v_pk_add_f32 v[136:137], v[136:137], v[138:139] neg_lo:[0,1] neg_hi:[0,1]
	v_lshlrev_b32_e32 v140, 16, v87
	v_pk_fma_f32 v[136:137], v[56:57], v[136:137], v[138:139]
	v_lshlrev_b32_e32 v138, 16, v91
	v_and_b32_e32 v139, 0xffff0000, v91
	v_and_b32_e32 v141, 0xffff0000, v87
	v_pk_add_f32 v[138:139], v[138:139], v[140:141] neg_lo:[0,1] neg_hi:[0,1]
	v_add3_u32 v214, s34, v155, v120
	v_pk_fma_f32 v[138:139], v[58:59], v[138:139], v[140:141]
	ds_write_b128 v142, v[136:139] offset:40976
	v_and_b32_e32 v140, 0xffff0000, v95
	v_and_b32_e32 v136, 0xffff0000, v99
	v_sub_f32_e32 v136, v136, v140
	v_fmac_f32_e32 v140, v19, v136
	v_lshlrev_b32_e32 v141, 16, v95
	v_lshlrev_b32_e32 v136, 16, v99
	v_sub_f32_e32 v136, v136, v141
	v_fmac_f32_e32 v141, v18, v136
	v_and_b32_e32 v142, 0xffff0000, v94
	v_and_b32_e32 v136, 0xffff0000, v98
	v_sub_f32_e32 v136, v136, v142
	v_fmac_f32_e32 v142, v17, v136
	v_and_b32_e32 v136, 0xffff0000, v93
	v_and_b32_e32 v137, 0xffff0000, v97
	v_sub_f32_e32 v137, v137, v136
	v_fmac_f32_e32 v136, v15, v137
	v_lshlrev_b32_e32 v137, 16, v93
	v_lshlrev_b32_e32 v138, 16, v97
	v_sub_f32_e32 v138, v138, v137
	v_fmac_f32_e32 v137, v14, v138
	v_and_b32_e32 v138, 0xffff0000, v92
	v_and_b32_e32 v139, 0xffff0000, v96
	v_sub_f32_e32 v139, v139, v138
	v_fmac_f32_e32 v138, v13, v139
	v_lshlrev_b32_e32 v139, 16, v92
	v_sub_f32_e32 v145, v145, v139
	v_fmac_f32_e32 v139, v12, v145
	v_add_f32_e32 v139, v139, v139
	v_add_f32_e32 v138, v138, v138
	v_mul_f32_e32 v139, 0x3fb8aa3b, v139
	v_mul_f32_e32 v138, 0x3fb8aa3b, v138
	v_add_f32_e32 v137, v137, v137
	v_add_f32_e32 v136, v136, v136
	v_exp_f32_e32 v139, v139
	v_exp_f32_e32 v138, v138
	v_mul_f32_e32 v137, 0x3fb8aa3b, v137
	v_mul_f32_e32 v136, 0x3fb8aa3b, v136
	v_exp_f32_e32 v137, v137
	v_exp_f32_e32 v136, v136
	v_add_f32_e32 v139, 1.0, v139
	v_add_f32_e32 v138, 1.0, v138
	v_add_f32_e32 v145, 1.0, v137
	v_add_f32_e32 v146, 1.0, v136
	v_rcp_f32_e64 v137, -v138
	v_rcp_f32_e64 v136, -v139
	v_rcp_f32_e64 v139, -v146
	v_add_f32_e32 v141, v141, v141
	v_add_f32_e32 v140, v140, v140
	v_pk_fma_f32 v[136:137], v[136:137], 2.0, 1.0 op_sel_hi:[1,0,0]
	v_mul_f32_e32 v141, 0x3fb8aa3b, v141
	v_bfe_u32 v146, v137, 16, 1
	v_bfe_u32 v147, v136, 16, 1
	v_add3_u32 v147, v136, v147, s89
	v_add3_u32 v146, v137, v146, s89
	v_add_f32_e32 v136, v143, v143
	v_add_f32_e32 v137, v142, v142
	v_mul_f32_e32 v136, 0x3fb8aa3b, v136
	v_mul_f32_e32 v137, 0x3fb8aa3b, v137
	v_mul_f32_e32 v140, 0x3fb8aa3b, v140
	v_exp_f32_e32 v136, v136
	v_exp_f32_e32 v137, v137
	v_exp_f32_e32 v141, v141
	v_exp_f32_e32 v140, v140
	v_rcp_f32_e64 v138, -v145
	v_add_f32_e32 v136, 1.0, v136
	v_add_f32_e32 v137, 1.0, v137
	v_add_f32_e32 v142, 1.0, v141
	v_add_f32_e32 v140, 1.0, v140
	v_rcp_f32_e64 v137, -v137
	v_rcp_f32_e64 v136, -v136
	v_rcp_f32_e64 v141, -v140
	v_rcp_f32_e64 v140, -v142
	v_pk_fma_f32 v[138:139], v[138:139], 2.0, 1.0 op_sel_hi:[1,0,0]
	v_pk_fma_f32 v[136:137], v[136:137], 2.0, 1.0 op_sel_hi:[1,0,0]
	v_bfe_u32 v144, v139, 16, 1
	v_bfe_u32 v145, v138, 16, 1
	v_add3_u32 v142, v138, v145, s89
	v_add3_u32 v143, v139, v144, s89
	v_pk_fma_f32 v[138:139], v[140:141], 2.0, 1.0 op_sel_hi:[1,0,0]
	v_bfe_u32 v144, v137, 16, 1
	v_bfe_u32 v140, v139, 16, 1
	v_bfe_u32 v141, v138, 16, 1
	v_bfe_u32 v145, v136, 16, 1
	v_add3_u32 v136, v136, v145, s89
	v_add3_u32 v137, v137, v144, s89
	v_add3_u32 v138, v138, v141, s89
	v_add3_u32 v139, v139, v140, s89
	v_perm_b32 v139, v139, v138, s90
	v_perm_b32 v138, v137, v136, s90
	v_perm_b32 v137, v143, v142, s90
	v_perm_b32 v136, v146, v147, s90
	ds_write_b128 v121, v[136:139]
	s_waitcnt vmcnt(1)
	v_lshlrev_b32_e32 v142, 16, v104
	v_lshlrev_b32_e32 v140, 16, v105
	v_and_b32_e32 v143, 0xffff0000, v104
	v_and_b32_e32 v141, 0xffff0000, v105
	v_lshlrev_b32_e32 v136, 16, v100
	v_lshlrev_b32_e32 v138, 16, v101
	v_and_b32_e32 v137, 0xffff0000, v100
	v_and_b32_e32 v139, 0xffff0000, v101
	v_sub_f32_e32 v141, v141, v139
	v_sub_f32_e32 v140, v140, v138
	v_sub_f32_e32 v143, v143, v137
	v_sub_f32_e32 v142, v142, v136
	v_pk_fma_f32 v[136:137], v[60:61], v[142:143], v[136:137]
	v_pk_fma_f32 v[138:139], v[62:63], v[140:141], v[138:139]
	v_bfe_u32 v142, v137, 16, 1
	v_bfe_u32 v140, v139, 16, 1
	v_bfe_u32 v141, v138, 16, 1
	v_bfe_u32 v143, v136, 16, 1
	v_add3_u32 v144, v136, v143, s89
	v_add3_u32 v145, v137, v142, s89
	v_add3_u32 v146, v138, v141, s89
	v_add3_u32 v147, v139, v140, s89
	v_lshlrev_b32_e32 v142, 16, v106
	v_lshlrev_b32_e32 v140, 16, v107
	v_and_b32_e32 v143, 0xffff0000, v106
	v_and_b32_e32 v141, 0xffff0000, v107
	v_lshlrev_b32_e32 v136, 16, v102
	v_lshlrev_b32_e32 v138, 16, v103
	v_and_b32_e32 v137, 0xffff0000, v102
	v_and_b32_e32 v139, 0xffff0000, v103
	v_sub_f32_e32 v141, v141, v139
	v_sub_f32_e32 v140, v140, v138
	v_sub_f32_e32 v143, v143, v137
	v_sub_f32_e32 v142, v142, v136
	v_pk_fma_f32 v[136:137], v[64:65], v[142:143], v[136:137]
	v_pk_fma_f32 v[138:139], v[66:67], v[140:141], v[138:139]
	v_bfe_u32 v142, v137, 16, 1
	v_bfe_u32 v140, v139, 16, 1
	v_bfe_u32 v141, v138, 16, 1
	v_bfe_u32 v143, v136, 16, 1
	v_add3_u32 v136, v136, v143, s89
	v_add3_u32 v137, v137, v142, s89
	v_add3_u32 v138, v138, v141, s89
	v_add3_u32 v139, v139, v140, s89
	v_perm_b32 v139, v139, v138, s90
	v_perm_b32 v138, v137, v136, s90
	v_perm_b32 v137, v147, v146, s90
	v_perm_b32 v136, v145, v144, s90
	ds_write_b128 v159, v[136:139]
	s_waitcnt lgkmcnt(0)
	ds_read_b128 v[136:139], v150
	ds_read_b128 v[140:143], v150 offset:64
	ds_read_b128 v[144:147], v160
	ds_read_b128 v[162:165], v160 offset:64
	s_waitcnt lgkmcnt(1)
	v_mfma_f32_16x16x32_bf16 v[144:147], v[136:139], v[144:147], 0
	v_lshl_add_u32 v215, v156, 2, s34
	v_lshl_add_u32 v216, v156, 3, s34
	s_waitcnt lgkmcnt(0)
	v_mfma_f32_16x16x32_bf16 v[144:147], v[140:143], v[162:165], v[144:147]
	ds_read_b128 v[162:165], v160 offset:2304
	ds_read_b128 v[166:169], v160 offset:2368
	s_waitcnt lgkmcnt(1)
	v_mfma_f32_16x16x32_bf16 v[162:165], v[136:139], v[162:165], 0
	s_waitcnt lgkmcnt(0)
	v_mfma_f32_16x16x32_bf16 v[162:165], v[140:143], v[166:169], v[162:165]
	ds_read_b128 v[166:169], v160 offset:4608
	ds_read_b128 v[170:173], v160 offset:4672
	s_waitcnt lgkmcnt(1)
	v_mfma_f32_16x16x32_bf16 v[166:169], v[136:139], v[166:169], 0
	s_waitcnt lgkmcnt(0)
	v_mfma_f32_16x16x32_bf16 v[166:169], v[140:143], v[170:173], v[166:169]
	ds_read_b128 v[170:173], v160 offset:6912
	ds_read_b128 v[174:177], v160 offset:6976
	s_waitcnt lgkmcnt(1)
	v_mfma_f32_16x16x32_bf16 v[136:139], v[136:139], v[170:173], 0
	ds_read_b128 v[170:173], v151
	s_nop 2
	v_cndmask_b32_e64 v144, v144, v166, s[0:1]
	v_add_f32_e32 v144, v124, v144
	s_waitcnt lgkmcnt(1)
	v_mfma_f32_16x16x32_bf16 v[136:139], v[140:143], v[174:177], v[136:139]
	ds_read_b128 v[140:143], v151 offset:64
	ds_read_b128 v[174:177], v160 offset:9216
	ds_read_b128 v[178:181], v160 offset:9280
	v_mul_f32_e32 v144, 0xbfb8aa3b, v144
	v_exp_f32_e32 v144, v144
	s_waitcnt lgkmcnt(1)
	v_mfma_f32_16x16x32_bf16 v[174:177], v[170:173], v[174:177], 0
	v_cndmask_b32_e64 v145, v145, v167, s[0:1]
	v_add_f32_e32 v144, 1.0, v144
	v_rcp_f32_e32 v144, v144
	s_waitcnt lgkmcnt(0)
	v_mfma_f32_16x16x32_bf16 v[174:177], v[140:143], v[178:181], v[174:177]
	ds_read_b128 v[178:181], v160 offset:11520
	ds_read_b128 v[184:187], v160 offset:11584
	v_add_f32_e32 v145, v124, v145
	v_mul_f32_e32 v144, 0xbf1b4598, v144
	s_waitcnt lgkmcnt(1)
	v_mfma_f32_16x16x32_bf16 v[178:181], v[170:173], v[178:181], 0
	v_mul_f32_e32 v144, 0x3fb8aa3b, v144
	v_mul_f32_e32 v145, 0xbfb8aa3b, v145
	v_exp_f32_e32 v144, v144
	s_waitcnt lgkmcnt(0)
	v_mfma_f32_16x16x32_bf16 v[178:181], v[140:143], v[184:187], v[178:181]
	ds_read_b128 v[184:187], v160 offset:13824
	ds_read_b128 v[188:191], v160 offset:13888
	v_exp_f32_e32 v145, v145
	v_cndmask_b32_e64 v147, v147, v169, s[0:1]
	s_waitcnt lgkmcnt(1)
	v_mfma_f32_16x16x32_bf16 v[184:187], v[170:173], v[184:187], 0
	v_cndmask_b32_e64 v146, v146, v168, s[0:1]
	v_lshl_add_u32 v169, v152, 2, s34
	v_cndmask_b32_e64 v136, v162, v136, s[0:1]
	s_waitcnt lgkmcnt(0)
	v_mfma_f32_16x16x32_bf16 v[184:187], v[140:143], v[188:191], v[184:187]
	ds_read_b128 v[188:191], v160 offset:16128
	ds_read_b128 v[192:195], v160 offset:16192
	v_add_f32_e32 v147, v124, v147
	v_add_f32_e32 v136, v125, v136
	s_waitcnt lgkmcnt(1)
	v_mfma_f32_16x16x32_bf16 v[170:173], v[170:173], v[188:191], 0
	s_nop 1
	v_cndmask_b32_e64 v167, v174, v184, s[0:1]
	v_add_f32_e32 v167, v126, v167
	v_mul_f32_e32 v167, 0xbfb8aa3b, v167
	v_exp_f32_e32 v167, v167
	v_mul_f32_e32 v147, 0xbfb8aa3b, v147
	v_mul_f32_e32 v136, 0xbfb8aa3b, v136
	s_waitcnt lgkmcnt(0)
	v_mfma_f32_16x16x32_bf16 v[140:143], v[140:143], v[192:195], v[170:173]
	v_add_f32_e32 v167, 1.0, v167
	v_rcp_f32_e32 v167, v167
	v_exp_f32_e32 v147, v147
	v_exp_f32_e32 v136, v136
	v_cndmask_b32_e64 v161, v177, v187, s[0:1]
	ds_write2st64_b32 v169, v144, v167 offset1:64
	v_mov_b32_e32 v246, v144
	v_add_f32_e32 v144, 1.0, v145
	v_add_f32_e32 v145, v124, v146
	v_mul_f32_e32 v145, 0xbfb8aa3b, v145
	v_exp_f32_e32 v145, v145
	v_cndmask_b32_e64 v166, v176, v186, s[0:1]
	v_cndmask_b32_e64 v168, v175, v185, s[0:1]
	v_add_f32_e32 v147, 1.0, v147
	v_add_f32_e32 v145, 1.0, v145
	v_cndmask_b32_e64 v137, v163, v137, s[0:1]
	v_add_f32_e32 v136, 1.0, v136
	v_cndmask_b32_e64 v140, v178, v140, s[0:1]
	v_rcp_f32_e32 v144, v144
	v_rcp_f32_e32 v145, v145
	v_add_f32_e32 v146, v126, v168
	v_add_f32_e32 v166, v126, v166
	v_rcp_f32_e32 v147, v147
	v_add_f32_e32 v161, v126, v161
	v_rcp_f32_e32 v136, v136
	v_add_f32_e32 v140, v127, v140
	v_add_f32_e32 v137, v125, v137
	v_mul_f32_e32 v146, 0xbfb8aa3b, v146
	v_mul_f32_e32 v166, 0xbfb8aa3b, v166
	v_mul_f32_e32 v161, 0xbfb8aa3b, v161
	v_mul_f32_e32 v140, 0xbfb8aa3b, v140
	v_mul_f32_e32 v137, 0xbfb8aa3b, v137
	v_exp_f32_e32 v146, v146
	v_exp_f32_e32 v166, v166
	v_exp_f32_e32 v161, v161
	v_exp_f32_e32 v140, v140
	v_exp_f32_e32 v137, v137
	v_mul_f32_e32 v144, 0xbf1b4598, v144
	v_mul_f32_e32 v145, 0xbf1b4598, v145
	v_mul_f32_e32 v147, 0xbf1b4598, v147
	v_mul_f32_e32 v136, 0xbf1b4598, v136
	v_mul_f32_e32 v144, 0x3fb8aa3b, v144
	v_mul_f32_e32 v145, 0x3fb8aa3b, v145
	v_mul_f32_e32 v147, 0x3fb8aa3b, v147
	v_mul_f32_e32 v136, 0x3fb8aa3b, v136
	v_exp_f32_e32 v144, v144
	v_exp_f32_e32 v145, v145
	v_add_f32_e32 v166, 1.0, v166
	v_exp_f32_e32 v147, v147
	v_add_f32_e32 v161, 1.0, v161
	v_add_f32_e32 v146, 1.0, v146
	v_exp_f32_e32 v136, v136
	v_add_f32_e32 v140, 1.0, v140
	v_add_f32_e32 v137, 1.0, v137
	v_rcp_f32_e32 v166, v166
	v_rcp_f32_e32 v161, v161
	v_rcp_f32_e32 v146, v146
	v_rcp_f32_e32 v140, v140
	v_rcp_f32_e32 v137, v137
	v_mul_f32_e32 v144, v144, v246
	v_mul_f32_e32 v145, v145, v144
	v_mul_f32_e32 v147, v147, v145
	v_mov_b32_e32 v247, v136
	ds_write2st64_b32 v169, v145, v147 offset0:2 offset1:3
	ds_write2st64_b32 v169, v166, v161 offset0:66 offset1:67
	v_cndmask_b32_e64 v138, v164, v138, s[0:1]
	ds_write2_b32 v169, v136, v144 offset0:16 offset1:64
	v_add_u32_e32 v136, 0x4000, v169
	v_cndmask_b32_e64 v139, v165, v139, s[0:1]
	ds_write2_b32 v136, v140, v146 offset0:16 offset1:64
	v_mul_f32_e32 v136, 0xbf1b4598, v137
	v_add_f32_e32 v137, v125, v138
	v_mul_f32_e32 v137, 0xbfb8aa3b, v137
	v_add_f32_e32 v139, v125, v139
	v_exp_f32_e32 v137, v137
	v_mul_f32_e32 v139, 0xbfb8aa3b, v139
	v_exp_f32_e32 v139, v139
	v_cndmask_b32_e64 v141, v179, v141, s[0:1]
	v_add_f32_e32 v137, 1.0, v137
	v_cndmask_b32_e64 v143, v181, v143, s[0:1]
	v_cndmask_b32_e64 v142, v180, v142, s[0:1]
	v_add_f32_e32 v138, v127, v141
	v_rcp_f32_e32 v137, v137
	v_add_f32_e32 v139, 1.0, v139
	v_mul_f32_e32 v138, 0xbfb8aa3b, v138
	v_add_f32_e32 v140, v127, v142
	v_rcp_f32_e32 v139, v139
	v_add_f32_e32 v141, v127, v143
	v_exp_f32_e32 v138, v138
	v_mul_f32_e32 v140, 0xbfb8aa3b, v140
	v_mul_f32_e32 v141, 0xbfb8aa3b, v141
	v_exp_f32_e32 v140, v140
	v_exp_f32_e32 v141, v141
	v_mul_f32_e32 v137, 0xbf1b4598, v137
	v_mul_f32_e32 v136, 0x3fb8aa3b, v136
	v_mul_f32_e32 v137, 0x3fb8aa3b, v137
	v_mul_f32_e32 v139, 0xbf1b4598, v139
	v_exp_f32_e32 v136, v136
	v_add_f32_e32 v138, 1.0, v138
	v_exp_f32_e32 v137, v137
	v_mul_f32_e32 v139, 0x3fb8aa3b, v139
	v_rcp_f32_e32 v138, v138
	v_add_f32_e32 v140, 1.0, v140
	v_exp_f32_e32 v139, v139
	v_add_f32_e32 v141, 1.0, v141
	v_rcp_f32_e32 v140, v140
	v_rcp_f32_e32 v141, v141
	v_lshl_add_u32 v142, v153, 2, s34
	v_mul_f32_e32 v136, v136, v247
	v_mul_f32_e32 v137, v137, v136
	v_mul_f32_e32 v139, v139, v137
	ds_write2st64_b32 v142, v136, v137 offset0:1 offset1:2
	ds_write2st64_b32 v142, v139, v138 offset0:3 offset1:65
	ds_write2st64_b32 v142, v140, v141 offset0:66 offset1:67
	s_waitcnt lgkmcnt(0)
	v_lshl_add_u32 v161, v154, 2, s34
	v_add_u32_e32 v244, 0xffffff00, v161
	ds_read_b128 v[228:231], v244
	ds_read_b128 v[232:235], v244 offset:16
	v_mbcnt_lo_u32_b32 v245, -1, 0
	v_mbcnt_hi_u32_b32 v245, -1, v245
	v_and_b32_e32 v245, 24, v245
	v_cmp_ne_u32_e64 s[44:45], 0, v245
	ds_read_b128 v[136:139], v161 offset:32768
	ds_read_b128 v[140:143], v161
	ds_read_b128 v[144:147], v161 offset:16
	ds_read_b128 v[162:165], v161 offset:32784
	s_add_i32 s34, s6, 3
	s_cmp_ge_u32 s34, s43
	s_waitcnt lgkmcnt(2)
	v_mul_f32_e32 v206, v136, v140
	v_mul_f32_e32 v207, v137, v141
	v_mul_f32_e32 v208, v138, v142
	v_mul_f32_e32 v209, v139, v143
	s_waitcnt lgkmcnt(0)
	v_mul_f32_e32 v210, v162, v144
	v_mul_f32_e32 v211, v163, v145
	v_mul_f32_e32 v212, v164, v146
	v_mul_f32_e32 v213, v165, v147
	v_rcp_f32_e32 v220, v140
	v_rcp_f32_e32 v221, v141
	v_rcp_f32_e32 v222, v142
	v_rcp_f32_e32 v223, v143
	v_rcp_f32_e32 v224, v144
	v_rcp_f32_e32 v225, v145
	v_rcp_f32_e32 v226, v146
	v_rcp_f32_e32 v227, v147
	v_cndmask_b32_e64 v228, 1.0, v228, s[44:45]
	v_cndmask_b32_e64 v229, 1.0, v229, s[44:45]
	v_cndmask_b32_e64 v230, 1.0, v230, s[44:45]
	v_cndmask_b32_e64 v231, 1.0, v231, s[44:45]
	v_cndmask_b32_e64 v232, 1.0, v232, s[44:45]
	v_cndmask_b32_e64 v233, 1.0, v233, s[44:45]
	v_cndmask_b32_e64 v234, 1.0, v234, s[44:45]
	v_cndmask_b32_e64 v235, 1.0, v235, s[44:45]
	ds_read_b128 v[140:143], v161 offset:16384
	ds_read_b128 v[144:147], v161 offset:16400
	ds_read_b128 v[166:169], v161 offset:24576
	ds_read_b128 v[170:173], v161 offset:24592
	s_waitcnt lgkmcnt(3)
	v_pk_add_f32 v[186:187], v[140:141], -1.0 op_sel_hi:[1,0]
	s_nop 0
	v_pk_fma_f32 v[186:187], v[28:29], v[186:187], 1.0 op_sel_hi:[1,1,0]
	s_waitcnt lgkmcnt(1)
	v_pk_mul_f32 v[184:185], v[20:21], v[166:167]
	v_pk_mul_f32 v[166:167], v[166:167], v[186:187]
	v_add_f32_e32 v187, -1.0, v142
	v_mov_b32_e32 v186, v168
	v_pk_mul_f32 v[198:199], v[22:23], v[186:187]
	v_add_f32_e32 v175, -1.0, v144
	s_waitcnt lgkmcnt(0)
	v_mov_b32_e32 v174, v170
	v_add_f32_e32 v191, -1.0, v143
	v_mov_b32_e32 v190, v169
	v_mov_b32_e32 v200, v184
	v_mov_b32_e32 v201, v198
	v_pk_mul_f32 v[176:177], v[24:25], v[174:175]
	v_pk_mul_f32 v[192:193], v[30:31], v[190:191]
	v_pk_mul_f32 v[200:201], v[200:201], v[200:201]
	v_mov_b32_e32 v188, v142
	v_mov_b32_e32 v194, v192
	v_mov_b32_e32 v195, v176
	v_fma_f32 v142, v185, v185, v200
	v_pk_mul_f32 v[194:195], v[194:195], v[194:195]
	v_add_f32_e32 v142, v142, v201
	v_add_f32_e32 v203, -1.0, v145
	v_mov_b32_e32 v202, v171
	v_add_f32_e32 v142, v142, v194
	v_pk_mul_f32 v[178:179], v[26:27], v[172:173]
	v_pk_mul_f32 v[204:205], v[32:33], v[202:203]
	v_add_f32_e32 v142, v142, v195
	v_pk_mul_f32 v[180:181], v[178:179], v[178:179]
	v_fmac_f32_e32 v142, v204, v204
	v_add_f32_e32 v142, v142, v180
	v_add_f32_e32 v142, v142, v181
	v_mov_b32_e32 v189, v168
	v_mov_b32_e32 v168, v143
	v_add_f32_dpp v142, v142, v142 quad_perm:[1,0,3,2] row_mask:0xf bank_mask:0xf bound_ctrl:1
	v_mov_b32_e32 v194, v144
	v_mul_f32_e32 v144, v137, v167
	v_add_f32_dpp v142, v142, v142 quad_perm:[2,3,0,1] row_mask:0xf bank_mask:0xf bound_ctrl:1
	v_mov_b32_e32 v180, v139
	v_mov_b32_e32 v195, v170
	v_add_f32_dpp v142, v142, v142 row_half_mirror row_mask:0xf bank_mask:0xf bound_ctrl:1
	v_max_f32_e32 v142, 0x179abe15, v142
	v_rsq_f32_e32 v182, v142
	v_mov_b32_e32 v170, v145
	v_mov_b32_e32 v145, v172
	v_mov_b32_e32 v172, v147
	v_pk_mul_f32 v[142:143], v[184:185], v[182:183] op_sel_hi:[1,0]
	v_mov_b32_e32 v185, v166
	v_pk_mul_f32 v[140:141], v[140:141], v[142:143]
	v_xor_b32_e32 v181, 0x80000000, v142
	v_mov_b32_e32 v184, v140
	v_mul_f32_e32 v142, v136, v166
	v_fma_f32 v200, v36, v142, 0
	v_pk_fma_f32 v[184:185], v[136:137], v[184:185], 0 op_sel_hi:[0,1,0]
	v_xor_b32_e32 v201, 0x80000000, v143
	v_mov_b32_e32 v142, v141
	v_mov_b32_e32 v143, v167
	v_pk_fma_f32 v[136:137], v[136:137], v[142:143], v[184:185] op_sel:[1,0,0]
	v_pk_mul_f32 v[142:143], v[198:199], v[182:183]
	v_pk_fma_f32 v[184:185], v[22:23], v[186:187], s[2:3]
	v_fmac_f32_e32 v200, v37, v144
	v_mov_b32_e32 v143, v185
	v_pk_mul_f32 v[184:185], v[188:189], v[142:143]
	v_xor_b32_e32 v188, 0x80000000, v142
	v_mul_f32_e32 v142, v185, v138
	v_fmac_f32_e32 v200, v38, v142
	v_pk_mul_f32 v[142:143], v[192:193], v[182:183]
	v_pk_fma_f32 v[186:187], v[30:31], v[190:191], s[2:3]
	v_pk_fma_f32 v[136:137], v[184:185], v[138:139], v[136:137] op_sel_hi:[1,0,1]
	v_mov_b32_e32 v143, v187
	v_pk_mul_f32 v[186:187], v[168:169], v[142:143]
	v_xor_b32_e32 v189, 0x80000000, v142
	v_mov_b32_e32 v142, v184
	v_mov_b32_e32 v143, v186
	v_mul_f32_e32 v138, v187, v139
	v_pk_mul_f32 v[236:237], v[140:141], v[220:221]
	v_pk_mul_f32 v[238:239], v[142:143], v[222:223]
	ds_write_b128 v161, v[236:239] offset:16384
	v_fmac_f32_e32 v200, v39, v138
	v_pk_mul_f32 v[138:139], v[176:177], v[182:183]
	v_pk_fma_f32 v[140:141], v[24:25], v[174:175], s[2:3]
	v_mov_b32_e32 v168, v185
	v_mov_b32_e32 v139, v141
	v_mov_b32_e32 v169, v187
	v_pk_mul_f32 v[142:143], v[194:195], v[138:139]
	v_pk_mul_f32 v[240:241], v[166:167], v[220:221]
	v_pk_mul_f32 v[242:243], v[168:169], v[222:223]
	ds_write_b128 v161, v[240:243] offset:24576
	v_pk_fma_f32 v[136:137], v[186:187], v[180:181], v[136:137] op_sel_hi:[1,0,1]
	v_xor_b32_e32 v166, 0x80000000, v138
	v_mul_f32_e32 v138, v143, v162
	v_fmac_f32_e32 v200, v40, v138
	v_pk_fma_f32 v[138:139], v[142:143], v[162:163], v[136:137] op_sel_hi:[1,0,1]
	v_pk_mul_f32 v[140:141], v[204:205], v[182:183]
	v_pk_fma_f32 v[136:137], v[32:33], v[202:203], s[2:3]
	v_xor_b32_e32 v167, 0x80000000, v140
	v_mov_b32_e32 v141, v137
	v_pk_mul_f32 v[136:137], v[170:171], v[140:141]
	v_mul_f32_e64 v168, v178, -v182
	v_mul_f32_e32 v140, v137, v163
	v_fmac_f32_e32 v200, v41, v140
	v_add_f32_e32 v140, -1.0, v146
	v_fma_f32 v141, v34, v140, 1.0
	v_mov_b32_e32 v144, v146
	v_xor_b32_e32 v140, 0x80000000, v168
	v_pk_fma_f32 v[138:139], v[136:137], v[162:163], v[138:139] op_sel:[0,1,0]
	v_pk_mul_f32 v[144:145], v[144:145], v[140:141]
	s_nop 0
	v_mul_f32_e32 v140, v145, v164
	v_pk_fma_f32 v[162:163], v[144:145], v[164:165], v[138:139] op_sel_hi:[1,0,1]
	v_add_f32_e32 v138, -1.0, v147
	v_mul_f32_e64 v164, v179, -v182
	v_fma_f32 v139, v35, v138, 1.0
	v_xor_b32_e32 v138, 0x80000000, v164
	v_pk_mul_f32 v[146:147], v[172:173], v[138:139]
	v_fmac_f32_e32 v200, v42, v140
	v_mov_b32_e32 v138, v142
	v_mov_b32_e32 v139, v136
	v_mov_b32_e32 v140, v144
	v_mov_b32_e32 v141, v146
	v_pk_mul_f32 v[236:237], v[138:139], v[224:225]
	v_pk_mul_f32 v[238:239], v[140:141], v[226:227]
	ds_write_b128 v161, v[236:239] offset:16400
	v_mov_b32_e32 v136, v143
	v_mov_b32_e32 v138, v145
	v_mov_b32_e32 v139, v147
	v_pk_mul_f32 v[240:241], v[136:137], v[224:225]
	v_pk_mul_f32 v[242:243], v[138:139], v[226:227]
	ds_write_b128 v161, v[240:243] offset:24592
	v_mov_b32_e32 v136, v165
	v_mul_f32_e32 v137, v147, v165
	v_fmac_f32_e32 v200, v43, v137
	v_pk_fma_f32 v[144:145], v[146:147], v[136:137], v[162:163] op_sel_hi:[1,0,1]
	v_mul_f32_e32 v236, v181, v228
	v_mul_f32_e32 v237, v201, v229
	v_cvt_pk_bf16_f32 v136, v236, v237
	v_mul_f32_e32 v236, v188, v230
	v_mul_f32_e32 v237, v189, v231
	v_cvt_pk_bf16_f32 v137, v236, v237
	v_mul_f32_e32 v236, v166, v232
	v_mul_f32_e32 v237, v167, v233
	v_cvt_pk_bf16_f32 v138, v236, v237
	v_mul_f32_e32 v236, v168, v234
	v_mul_f32_e32 v237, v164, v235
	v_cvt_pk_bf16_f32 v139, v236, v237
	v_cvt_pk_bf16_f32 v140, v206, v207
	v_cvt_pk_bf16_f32 v141, v208, v209
	v_cvt_pk_bf16_f32 v142, v210, v211
	v_cvt_pk_bf16_f32 v143, v212, v213
	ds_write_b128 v214, v[136:139] offset:8192
	ds_write_b128 v214, v[140:143] offset:12288
	v_add_f32_dpp v136, v200, v200 quad_perm:[1,0,3,2] row_mask:0xf bank_mask:0xf bound_ctrl:1
	v_mov_b32_dpp v137, v145 quad_perm:[1,0,3,2] row_mask:0xf bank_mask:0xf bound_ctrl:1
	s_nop 0
	v_add_f32_dpp v136, v136, v136 quad_perm:[2,3,0,1] row_mask:0xf bank_mask:0xf bound_ctrl:1
	s_nop 1
	v_add_f32_dpp v140, v136, v136 row_half_mirror row_mask:0xf bank_mask:0xf bound_ctrl:1
	v_mov_b32_dpp v136, v144 quad_perm:[1,0,3,2] row_mask:0xf bank_mask:0xf bound_ctrl:1
	v_pk_add_f32 v[136:137], v[144:145], v[136:137]
	ds_write_b32 v215, v140 offset:57216
	s_nop 0
	v_mov_b32_dpp v138, v136 quad_perm:[2,3,0,1] row_mask:0xf bank_mask:0xf bound_ctrl:1
	v_mov_b32_dpp v139, v137 quad_perm:[2,3,0,1] row_mask:0xf bank_mask:0xf bound_ctrl:1
	v_pk_add_f32 v[136:137], v[136:137], v[138:139]
	s_nop 1
	v_mov_b32_dpp v138, v136 row_half_mirror row_mask:0xf bank_mask:0xf bound_ctrl:1
	v_mov_b32_dpp v139, v137 row_half_mirror row_mask:0xf bank_mask:0xf bound_ctrl:1
	v_pk_add_f32 v[136:137], v[136:137], v[138:139]
	ds_write_b64 v216, v[136:137] offset:57216
	s_waitcnt vmcnt(0)
	s_cbranch_scc1 .LBB0_784
	v_lshl_add_u64 v[84:85], v[128:129], 0, s[4:5]
	v_add_co_u32_e32 v72, vcc, 0x239a5000, v84
	v_lshl_add_u64 v[92:93], v[130:131], 0, s[4:5]
	s_nop 0
	v_addc_co_u32_e32 v73, vcc, 0, v85, vcc
	v_add_co_u32_e32 v74, vcc, 0x239a3000, v84
	v_lshl_add_u64 v[80:81], v[132:133], 0, s[4:5]
	s_nop 0
	v_addc_co_u32_e32 v75, vcc, 0, v85, vcc
	v_add_co_u32_e32 v88, vcc, 0x239a4000, v84
	v_lshl_add_u64 v[86:87], v[134:135], 0, s[4:5]
	s_nop 0
	v_addc_co_u32_e32 v89, vcc, 0, v85, vcc
	v_add_co_u32_e32 v96, vcc, 0x239a6000, v92
	global_load_dwordx4 v[68:71], v[72:73], off
	global_load_dwordx4 v[76:79], v[72:73], off offset:2048
	v_addc_co_u32_e32 v97, vcc, 0, v93, vcc
	v_add_co_u32_e32 v104, vcc, 0x239a4000, v92
	global_load_dwordx4 v[72:75], v[74:75], off offset:1792
	s_nop 0
	global_load_dwordx4 v[80:83], v[80:81], off
	v_addc_co_u32_e32 v105, vcc, 0, v93, vcc
	global_load_dwordx4 v[84:87], v[86:87], off
	s_nop 0
	global_load_dwordx4 v[88:91], v[88:89], off offset:1792
	s_nop 0
	global_load_dwordx4 v[92:95], v[96:97], off offset:2048
	global_load_dwordx4 v[100:103], v[96:97], off offset:2176
	s_nop 0
	global_load_dwordx4 v[96:99], v[104:105], off offset:3840
	s_nop 0
	global_load_dwordx4 v[104:107], v[104:105], off offset:3968
	s_branch .LBB0_784

; DI void scan_item(const Params& p, char* smem, int b, int h, bool prompt, const int g_wave) {
;     ...
; #pragma unroll 1
;     for (int k = 0; k < nch; ++k) {
;       const char* set = smem + (k & 1) * SETB;
;       const float* bW = (const float*)set + 8 * g;
;       const char* bA = set + abf_off;
;       const float* bV = (const float*)(set + 40960) + irow;
;       float* Yp = (float*)(set + 49152) + irow;
;       const float2* BK = (const float2*)(set + 57472);
;     ...
;       f32x4v Pw0, Pw1, Pw2, Pw3, Pb0, Pb1, Pb2, Pb3, Pk0, Pk1, Pk2, Pk3; bf16x8 Pa0, Pa1; float Pv; float2 Ps;
;       f32x4v Qw0, Qw1, Qw2, Qw3, Qb0, Qb1, Qb2, Qb3, Qk0, Qk1, Qk2, Qk3; bf16x8 Qa0, Qa1; float Qv; float2 Qs;
;       LOADV(P, 0);
; #pragma unroll 1
;       for (int t = 0; t < 32; t += 2) {
;         LOADV(Q, t + 1);
;         STEP(P, t);
;         LOADV(P, t + 2);
;         STEP(Q, t + 1);
;       }
.LBB0_795:
	s_bitcmp1_b32 s0, 0
	s_cselect_b32 s4, 0xe180, 0
	s_add_i32 s1, s4, 16
	v_add_u32_e32 v88, s1, v85
	v_add_u32_e32 v86, s1, v83
	v_add_u32_e32 v26, s1, v27
	v_add_u32_e32 v89, s1, v77
	v_add_u32_e32 v87, s1, v84
	s_add_i32 s1, s1, 0xe080
	v_mov_b32_e32 v111, s1
	s_cmp_lg_u32 s0, 0
	s_cbranch_scc1 .Lsc_newfmt
	ds_read_b128 v[52:55], v88
	ds_read_b128 v[40:43], v88 offset:64
	ds_read_b128 v[28:31], v88 offset:128
	ds_read_b128 v[20:23], v88 offset:192
	ds_read2_b32 v[60:61], v86 offset0:0 offset1:16
	ds_read2_b32 v[62:63], v86 offset0:32 offset1:48
	ds_read2_b32 v[32:33], v26 offset0:0 offset1:16
	ds_read2_b32 v[34:35], v26 offset0:32 offset1:48
	ds_read_b64 v[72:73], v89
	ds_read_b64 v[74:75], v89 offset:32
	ds_read_b64 v[68:69], v89 offset:64
	ds_read_b64 v[70:71], v89 offset:96
	ds_read_b32 v78, v87
	ds_read_b64 v[80:81], v111
	s_mov_b32 s4, -2
.Lsc_loopA:
	ds_read_b128 v[90:93], v88 offset:256
	ds_read_b128 v[94:97], v88 offset:320
	ds_read_b128 v[98:101], v88 offset:384
	ds_read_b128 v[102:105], v88 offset:448
	ds_read2_b32 v[106:107], v86 offset0:64 offset1:80
	ds_read2_b32 v[108:109], v86 offset0:96 offset1:112
	ds_read2_b32 v[36:37], v26 offset0:64 offset1:80
	ds_read2_b32 v[38:39], v26 offset0:96 offset1:112
	ds_read_b64 v[138:139], v89 offset:128
	ds_read_b64 v[140:141], v89 offset:160
	ds_read_b64 v[142:143], v89 offset:192
	ds_read_b64 v[144:145], v89 offset:224
	ds_read_b32 v154, v87 offset:256
	ds_read_b64 v[156:157], v111 offset:8
	v_cvt_pk_bf16_f32 v146, v16, v17
	v_cvt_pk_bf16_f32 v147, v18, v19
	v_cvt_pk_bf16_f32 v148, v12, v13
	v_cvt_pk_bf16_f32 v149, v14, v15
	v_cvt_pk_bf16_f32 v150, v4, v5
	v_cvt_pk_bf16_f32 v151, v6, v7
	v_cvt_pk_bf16_f32 v152, v8, v9
	v_cvt_pk_bf16_f32 v153, v10, v11
	s_waitcnt lgkmcnt(14)
	v_mfma_f32_16x16x32_bf16 v[72:75], v[72:75], v[146:149], 0
	v_mfma_f32_16x16x32_bf16 v[68:71], v[68:71], v[150:153], v[72:75]
	v_pk_mul_f32 v[16:17], v[16:17], v[52:53]
	v_pk_mul_f32 v[18:19], v[18:19], v[54:55]
	v_pk_mul_f32 v[12:13], v[12:13], v[40:41]
	v_pk_mul_f32 v[14:15], v[14:15], v[42:43]
	v_pk_mul_f32 v[4:5], v[4:5], v[28:29]
	v_pk_mul_f32 v[6:7], v[6:7], v[30:31]
	v_pk_mul_f32 v[8:9], v[8:9], v[20:21]
	v_pk_mul_f32 v[10:11], v[10:11], v[22:23]
	v_mfma_f32_4x4x1_16b_f32 v[16:19], v32, v78, v[16:19]
	v_mfma_f32_4x4x1_16b_f32 v[12:15], v33, v78, v[12:15]
	v_mfma_f32_4x4x1_16b_f32 v[4:7], v34, v78, v[4:7]
	v_mfma_f32_4x4x1_16b_f32 v[8:11], v35, v78, v[8:11]
	v_fma_f32 v146, v78, v81, v69
	v_fmac_f32_e32 v146, v68, v80
	v_mfma_f32_4x4x1_16b_f32 v[16:19], v60, v68, v[16:19]
	v_mfma_f32_4x4x1_16b_f32 v[12:15], v61, v68, v[12:15]
	v_mfma_f32_4x4x1_16b_f32 v[4:7], v62, v68, v[4:7]
	v_mfma_f32_4x4x1_16b_f32 v[8:11], v63, v68, v[8:11]
	ds_write_b32 v87, v146 offset:8192
	ds_read_b128 v[52:55], v88 offset:512
	ds_read_b128 v[40:43], v88 offset:576
	ds_read_b128 v[28:31], v88 offset:640
	ds_read_b128 v[20:23], v88 offset:704
	ds_read2_b32 v[60:61], v86 offset0:128 offset1:144
	ds_read2_b32 v[62:63], v86 offset0:160 offset1:176
	ds_read2_b32 v[32:33], v26 offset0:128 offset1:144
	ds_read2_b32 v[34:35], v26 offset0:160 offset1:176
	ds_read_b64 v[72:73], v89 offset:256
	ds_read_b64 v[74:75], v89 offset:288
	ds_read_b64 v[68:69], v89 offset:320
	ds_read_b64 v[70:71], v89 offset:352
	ds_read_b32 v78, v87 offset:512
	ds_read_b64 v[80:81], v111 offset:16
	v_cvt_pk_bf16_f32 v146, v16, v17
	v_cvt_pk_bf16_f32 v147, v18, v19
	v_cvt_pk_bf16_f32 v148, v12, v13
	v_cvt_pk_bf16_f32 v149, v14, v15
	v_cvt_pk_bf16_f32 v150, v4, v5
	v_cvt_pk_bf16_f32 v151, v6, v7
	v_cvt_pk_bf16_f32 v152, v8, v9
	v_cvt_pk_bf16_f32 v153, v10, v11
	s_waitcnt lgkmcnt(14)
	v_mfma_f32_16x16x32_bf16 v[138:141], v[138:141], v[146:149], 0
	v_mfma_f32_16x16x32_bf16 v[142:145], v[142:145], v[150:153], v[138:141]
	v_pk_mul_f32 v[16:17], v[16:17], v[90:91]
	v_pk_mul_f32 v[18:19], v[18:19], v[92:93]
	v_pk_mul_f32 v[12:13], v[12:13], v[94:95]
	v_pk_mul_f32 v[14:15], v[14:15], v[96:97]
	v_pk_mul_f32 v[4:5], v[4:5], v[98:99]
	v_pk_mul_f32 v[6:7], v[6:7], v[100:101]
	v_pk_mul_f32 v[8:9], v[8:9], v[102:103]
	v_pk_mul_f32 v[10:11], v[10:11], v[104:105]
	v_mfma_f32_4x4x1_16b_f32 v[16:19], v36, v154, v[16:19]
	v_mfma_f32_4x4x1_16b_f32 v[12:15], v37, v154, v[12:15]
	v_mfma_f32_4x4x1_16b_f32 v[4:7], v38, v154, v[4:7]
	v_mfma_f32_4x4x1_16b_f32 v[8:11], v39, v154, v[8:11]
	v_fma_f32 v146, v154, v157, v143
	v_fmac_f32_e32 v146, v142, v156
	v_mfma_f32_4x4x1_16b_f32 v[16:19], v106, v142, v[16:19]
	v_mfma_f32_4x4x1_16b_f32 v[12:15], v107, v142, v[12:15]
	v_mfma_f32_4x4x1_16b_f32 v[4:7], v108, v142, v[4:7]
	v_mfma_f32_4x4x1_16b_f32 v[8:11], v109, v142, v[8:11]
	ds_write_b32 v87, v146 offset:8448
	s_add_i32 s4, s4, 2
	v_add_u32_e32 v88, 0x200, v88
	v_add_u32_e32 v86, 0x200, v86
	v_add_u32_e32 v26, 0x200, v26
	v_add_u32_e32 v89, 0x100, v89
	v_add_u32_e32 v87, 0x200, v87
	v_add_u32_e32 v111, 16, v111
	s_cmp_gt_u32 s4, 29
	s_cbranch_scc0 .Lsc_loopA
	s_branch .Lsc_chunk_end
.Lsc_newfmt:
	ds_read2_b32 v[60:61], v86 offset0:0 offset1:16
	ds_read2_b32 v[62:63], v86 offset0:32 offset1:48
	ds_read2_b32 v[32:33], v26 offset0:0 offset1:16
	ds_read2_b32 v[34:35], v26 offset0:32 offset1:48
	ds_read_b64 v[72:73], v89
	ds_read_b64 v[74:75], v89 offset:32
	ds_read_b64 v[68:69], v89 offset:64
	ds_read_b64 v[70:71], v89 offset:96
	ds_read_b32 v78, v87
	ds_read_b64 v[80:81], v111
	s_mov_b32 s4, -4
; DI void scan_item(const Params& p, char* smem, int b, int h, bool prompt, const int g_wave) {
;     ...
;       f32x4v Pw0, Pw1, Pw2, Pw3, Pb0, Pb1, Pb2, Pb3, Pk0, Pk1, Pk2, Pk3; bf16x8 Pa0, Pa1; float Pv; float2 Ps;
;       f32x4v Qw0, Qw1, Qw2, Qw3, Qb0, Qb1, Qb2, Qb3, Qk0, Qk1, Qk2, Qk3; bf16x8 Qa0, Qa1; float Qv; float2 Qs;
;       LOADV(P, 0);
; #pragma unroll 1
;       for (int t = 0; t < 32; t += 2) {
;         LOADV(Q, t + 1);
;         STEP(P, t);
;         LOADV(P, t + 2);
;         STEP(Q, t + 1);
;       }
.Lsc_loopB:
	ds_read_b128 v[52:55], v88 offset:768
	ds_read_b128 v[40:43], v88 offset:832
	ds_read_b128 v[28:31], v88 offset:896
	ds_read_b128 v[20:23], v88 offset:960
	ds_read2_b32 v[106:107], v86 offset0:64 offset1:80
	ds_read2_b32 v[108:109], v86 offset0:96 offset1:112
	ds_read2_b32 v[36:37], v26 offset0:64 offset1:80
	ds_read2_b32 v[38:39], v26 offset0:96 offset1:112
	ds_read_b64 v[138:139], v89 offset:128
	ds_read_b64 v[140:141], v89 offset:160
	ds_read_b64 v[142:143], v89 offset:192
	ds_read_b64 v[144:145], v89 offset:224
	ds_read_b32 v154, v87 offset:256
	ds_read_b64 v[156:157], v111 offset:8
	v_cvt_pk_bf16_f32 v146, v16, v17
	v_cvt_pk_bf16_f32 v147, v18, v19
	v_cvt_pk_bf16_f32 v148, v12, v13
	v_cvt_pk_bf16_f32 v149, v14, v15
	v_cvt_pk_bf16_f32 v150, v4, v5
	v_cvt_pk_bf16_f32 v151, v6, v7
	v_cvt_pk_bf16_f32 v152, v8, v9
	v_cvt_pk_bf16_f32 v153, v10, v11
	s_waitcnt lgkmcnt(10)
	v_mfma_f32_16x16x32_bf16 v[72:75], v[72:75], v[146:149], 0
	v_mfma_f32_16x16x32_bf16 v[68:71], v[68:71], v[150:153], v[72:75]
	v_mfma_f32_4x4x1_16b_f32 v[16:19], v32, v78, v[16:19]
	v_mfma_f32_4x4x1_16b_f32 v[12:15], v33, v78, v[12:15]
	v_mfma_f32_4x4x1_16b_f32 v[4:7], v34, v78, v[4:7]
	v_mfma_f32_4x4x1_16b_f32 v[8:11], v35, v78, v[8:11]
	s_nop 3
	v_fma_f32 v146, v78, v81, v69
	v_fmac_f32_e32 v146, v68, v80
	v_mfma_f32_4x4x1_16b_f32 v[16:19], v60, v68, v[16:19]
	v_mfma_f32_4x4x1_16b_f32 v[12:15], v61, v68, v[12:15]
	v_mfma_f32_4x4x1_16b_f32 v[4:7], v62, v68, v[4:7]
	v_mfma_f32_4x4x1_16b_f32 v[8:11], v63, v68, v[8:11]
	ds_write_b32 v87, v146 offset:8192
	ds_read2_b32 v[60:61], v86 offset0:128 offset1:144
	ds_read2_b32 v[62:63], v86 offset0:160 offset1:176
	ds_read2_b32 v[32:33], v26 offset0:128 offset1:144
	ds_read2_b32 v[34:35], v26 offset0:160 offset1:176
	ds_read_b64 v[72:73], v89 offset:256
	ds_read_b64 v[74:75], v89 offset:288
	ds_read_b64 v[68:69], v89 offset:320
	ds_read_b64 v[70:71], v89 offset:352
	ds_read_b32 v78, v87 offset:512
	ds_read_b64 v[80:81], v111 offset:16
	v_cvt_pk_bf16_f32 v146, v16, v17
	v_cvt_pk_bf16_f32 v147, v18, v19
	v_cvt_pk_bf16_f32 v148, v12, v13
	v_cvt_pk_bf16_f32 v149, v14, v15
	v_cvt_pk_bf16_f32 v150, v4, v5
	v_cvt_pk_bf16_f32 v151, v6, v7
	v_cvt_pk_bf16_f32 v152, v8, v9
	v_cvt_pk_bf16_f32 v153, v10, v11
	s_waitcnt lgkmcnt(10)
	v_mfma_f32_16x16x32_bf16 v[138:141], v[138:141], v[146:149], 0
	v_mfma_f32_16x16x32_bf16 v[142:145], v[142:145], v[150:153], v[138:141]
	v_mfma_f32_4x4x1_16b_f32 v[16:19], v36, v154, v[16:19]
	v_mfma_f32_4x4x1_16b_f32 v[12:15], v37, v154, v[12:15]
	v_mfma_f32_4x4x1_16b_f32 v[4:7], v38, v154, v[4:7]
	v_mfma_f32_4x4x1_16b_f32 v[8:11], v39, v154, v[8:11]
	s_nop 3
	v_fma_f32 v146, v154, v157, v143
	v_fmac_f32_e32 v146, v142, v156
	v_mfma_f32_4x4x1_16b_f32 v[16:19], v106, v142, v[16:19]
	v_mfma_f32_4x4x1_16b_f32 v[12:15], v107, v142, v[12:15]
	v_mfma_f32_4x4x1_16b_f32 v[4:7], v108, v142, v[4:7]
	v_mfma_f32_4x4x1_16b_f32 v[8:11], v109, v142, v[8:11]
	ds_write_b32 v87, v146 offset:8448
	ds_read2_b32 v[106:107], v86 offset0:192 offset1:208
	ds_read2_b32 v[108:109], v86 offset0:224 offset1:240
	ds_read2_b32 v[36:37], v26 offset0:192 offset1:208
	ds_read2_b32 v[38:39], v26 offset0:224 offset1:240
	ds_read_b64 v[138:139], v89 offset:384
	ds_read_b64 v[140:141], v89 offset:416
	ds_read_b64 v[142:143], v89 offset:448
	ds_read_b64 v[144:145], v89 offset:480
	ds_read_b32 v154, v87 offset:768
	ds_read_b64 v[156:157], v111 offset:24
	v_cvt_pk_bf16_f32 v146, v16, v17
	v_cvt_pk_bf16_f32 v147, v18, v19
	v_cvt_pk_bf16_f32 v148, v12, v13
	v_cvt_pk_bf16_f32 v149, v14, v15
	v_cvt_pk_bf16_f32 v150, v4, v5
	v_cvt_pk_bf16_f32 v151, v6, v7
	v_cvt_pk_bf16_f32 v152, v8, v9
	v_cvt_pk_bf16_f32 v153, v10, v11
	s_waitcnt lgkmcnt(10)
	v_mfma_f32_16x16x32_bf16 v[72:75], v[72:75], v[146:149], 0
	v_mfma_f32_16x16x32_bf16 v[68:71], v[68:71], v[150:153], v[72:75]
	v_mfma_f32_4x4x1_16b_f32 v[16:19], v32, v78, v[16:19]
	v_mfma_f32_4x4x1_16b_f32 v[12:15], v33, v78, v[12:15]
	v_mfma_f32_4x4x1_16b_f32 v[4:7], v34, v78, v[4:7]
	v_mfma_f32_4x4x1_16b_f32 v[8:11], v35, v78, v[8:11]
	s_nop 3
	v_fma_f32 v146, v78, v81, v69
	v_fmac_f32_e32 v146, v68, v80
	v_mfma_f32_4x4x1_16b_f32 v[16:19], v60, v68, v[16:19]
	v_mfma_f32_4x4x1_16b_f32 v[12:15], v61, v68, v[12:15]
	v_mfma_f32_4x4x1_16b_f32 v[4:7], v62, v68, v[4:7]
	v_mfma_f32_4x4x1_16b_f32 v[8:11], v63, v68, v[8:11]
	ds_write_b32 v87, v146 offset:8704
	v_add_u32_e32 v88, 0x400, v88
	v_add_u32_e32 v86, 0x400, v86
	v_add_u32_e32 v26, 0x400, v26
	v_add_u32_e32 v89, 0x200, v89
	v_add_u32_e32 v87, 0x400, v87
	v_add_u32_e32 v111, 32, v111
	s_nop 0
	ds_read2_b32 v[60:61], v86 offset0:0 offset1:16
	ds_read2_b32 v[62:63], v86 offset0:32 offset1:48
	ds_read2_b32 v[32:33], v26 offset0:0 offset1:16
	ds_read2_b32 v[34:35], v26 offset0:32 offset1:48
	ds_read_b64 v[72:73], v89
	ds_read_b64 v[74:75], v89 offset:32
	ds_read_b64 v[68:69], v89 offset:64
	ds_read_b64 v[70:71], v89 offset:96
	ds_read_b32 v78, v87
	ds_read_b64 v[80:81], v111
	v_cvt_pk_bf16_f32 v146, v16, v17
	v_cvt_pk_bf16_f32 v147, v18, v19
	v_cvt_pk_bf16_f32 v148, v12, v13
	v_cvt_pk_bf16_f32 v149, v14, v15
	v_cvt_pk_bf16_f32 v150, v4, v5
	v_cvt_pk_bf16_f32 v151, v6, v7
	v_cvt_pk_bf16_f32 v152, v8, v9
	v_cvt_pk_bf16_f32 v153, v10, v11
	s_waitcnt lgkmcnt(10)
	v_mfma_f32_16x16x32_bf16 v[138:141], v[138:141], v[146:149], 0
	v_mfma_f32_16x16x32_bf16 v[142:145], v[142:145], v[150:153], v[138:141]
	v_mfma_f32_4x4x1_16b_f32 v[16:19], v36, v154, v[16:19]
	v_mfma_f32_4x4x1_16b_f32 v[12:15], v37, v154, v[12:15]
	v_mfma_f32_4x4x1_16b_f32 v[4:7], v38, v154, v[4:7]
	v_mfma_f32_4x4x1_16b_f32 v[8:11], v39, v154, v[8:11]
	s_nop 3
	v_fma_f32 v146, v154, v157, v143
	v_fmac_f32_e32 v146, v142, v156
	v_mfma_f32_4x4x1_16b_f32 v[16:19], v106, v142, v[16:19]
	v_mfma_f32_4x4x1_16b_f32 v[12:15], v107, v142, v[12:15]
	v_mfma_f32_4x4x1_16b_f32 v[4:7], v108, v142, v[4:7]
	v_mfma_f32_4x4x1_16b_f32 v[8:11], v109, v142, v[8:11]
	ds_write_b32 v87, v146 offset:7936
	s_add_i32 s4, s4, 4
	s_cmp_gt_u32 s4, 27
	s_nop 1
	v_pk_mul_f32 v[16:17], v[16:17], v[52:53]
	v_pk_mul_f32 v[18:19], v[18:19], v[54:55]
	v_pk_mul_f32 v[12:13], v[12:13], v[40:41]
	v_pk_mul_f32 v[14:15], v[14:15], v[42:43]
	v_pk_mul_f32 v[4:5], v[4:5], v[28:29]
	v_pk_mul_f32 v[6:7], v[6:7], v[30:31]
	v_pk_mul_f32 v[8:9], v[8:9], v[20:21]
	v_pk_mul_f32 v[10:11], v[10:11], v[22:23]
	s_cbranch_scc0 .Lsc_loopB
; DI void scan_item(const Params& p, char* smem, int b, int h, bool prompt, const int g_wave) {
;     ...
;       asm volatile("s_waitcnt lgkmcnt(0)" ::: "memory");
;       __builtin_amdgcn_s_barrier();
;       asm volatile("" ::: "memory");
;     }
;     float* so = p.out + (prompt ? O_WKVP : O_WKVS) + ((size_t)(b * 16 + h) * 64 + irow) * 64 + 8 * g;
;     *(float4*)so = make_float4(S0[0].x, S0[0].y, S0[1].x, S0[1].y); *(float4*)(so + 4) = make_float4(S0[2].x, S0[2].y, S0[3].x, S0[3].y);
;     *(float4*)(so + 32) = make_float4(S1[0].x, S1[0].y, S1[1].x, S1[1].y); *(float4*)(so + 36) = make_float4(S1[2].x, S1[2].y, S1[3].x, S1[3].y);
.Lsc_chunk_end:
	s_waitcnt lgkmcnt(0)
	s_barrier
	s_add_i32 s0, s0, 1
	s_cmp_eq_u32 s0, s43
	s_cbranch_scc0 .LBB0_795
	s_and_b64 s[0:1], s[38:39], exec
	s_mov_b32 s0, 0x30200000
	s_cselect_b32 s0, s0, 0x30819000
	s_add_u32 s4, s70, s0
	s_addc_u32 s5, s71, 0
	s_ashr_i32 s43, s42, 31
	s_lshl_b64 s[0:1], s[42:43], 14
	s_add_u32 s0, s4, s0
	s_addc_u32 s1, s5, s1
	s_nop 7
	s_nop 3
	v_lshl_add_u64 v[20:21], s[0:1], 0, v[2:3]
	v_mov_b32_e32 v77, v3
	v_lshl_add_u64 v[20:21], v[20:21], 0, v[76:77]
	global_store_dwordx4 v[20:21], v[16:19], off
	global_store_dwordx4 v[20:21], v[12:15], off offset:64
	global_store_dwordx4 v[20:21], v[4:7], off offset:128
	global_store_dwordx4 v[20:21], v[8:11], off offset:192
	s_branch .LBB0_680
